# baseline (speedup 1.0000x reference)
; __device__ void prep_phase(KP p, char* shm) {
;   const int tid = tid_v();
;   {
;     const int wave = tid >> 6, lane = tid & 63;
;     for (int row = bid_s() * 8 + wave; row < S_; row += gridDim.x * 8) {
;       const float4* xr = (const float4*)(p->x_in + (size_t)row * D_);
;       float ss = 0.f;
; #pragma unroll
;       for (int i = 0; i < 8; ++i) {
;         float4 v = ld_nt16f((const float*)(xr + lane + 64 * i));
;         ss += v.x * v.x + v.y * v.y + v.z * v.z + v.w * v.w;
;         uint2 o; o.x = pack2(v.x, v.y); o.y = pack2(v.z, v.w);
;         *(uint2*)(p->xb + (size_t)row * D_ + (lane + 64 * i) * 4) = o;
;       }
;       ss = wave_sum(ss, lane);
;       if (lane < 32) p->rowss[(size_t)lane * S_ + row] = (lane == 0) ? ss : 0.f;
;     }
.LBB0_449:
	v_mov_b32_e32 v53, v210
	s_mov_b32 s4, s2
	v_ashrrev_i32_e32 v0, 6, v53
	s_nop 0
	v_lshl_add_u32 v0, s4, 3, v0
	v_cmp_gt_i32_e32 vcc, s71, v0
	s_and_saveexec_b64 s[8:9], vcc
	s_cbranch_execz .LBB0_454
	s_load_dwordx2 s[4:5], s[0:1], 0x0
	s_load_dwordx2 s[6:7], s[0:1], 0xb0
	v_and_b32_e32 v1, 63, v53
	v_lshlrev_b32_e32 v192, 4, v1
	v_lshlrev_b32_e32 v4, 2, v1
	s_waitcnt lgkmcnt(0)
	v_lshl_add_u64 v[2:3], s[4:5], 0, v[192:193]
	v_lshlrev_b32_e32 v8, 14, v1
	v_lshlrev_b32_e32 v192, 3, v1
	v_xor_b32_e32 v6, 0x80, v4
	v_cmp_gt_u32_e32 vcc, 32, v1
	v_cmp_eq_u32_e64 s[4:5], 0, v1
	v_lshl_add_u64 v[4:5], s[6:7], 0, v[192:193]
	s_mov_b64 s[10:11], 0
	v_lshlrev_b32_e32 v192, 2, v8
	s_load_dwordx2 s[12:13], s[0:1], 0xe8
	v_readfirstlane_b32 s14, v0
	s_waitcnt lgkmcnt(0)
	v_lshl_add_u64 v[44:45], s[12:13], 0, v[192:193]
	s_min_i32 s16, s14, s79
	s_lshl_b32 s6, s16, 13
	s_mov_b32 s7, 0
	s_add_u32 s10, s6, 0x1000
	s_mov_b32 s11, 0
	v_lshl_add_u64 v[46:47], v[2:3], 0, s[6:7]
	v_lshl_add_u64 v[48:49], v[2:3], 0, s[10:11]
	global_load_dwordx4 v[60:63], v[46:47], off nt
	global_load_dwordx4 v[64:67], v[46:47], off offset:1024 nt
	global_load_dwordx4 v[68:71], v[46:47], off offset:2048 nt
	global_load_dwordx4 v[72:75], v[46:47], off offset:3072 nt
	global_load_dwordx4 v[76:79], v[48:49], off nt
	global_load_dwordx4 v[80:83], v[48:49], off offset:1024 nt
	global_load_dwordx4 v[84:87], v[48:49], off offset:2048 nt
	global_load_dwordx4 v[88:91], v[48:49], off offset:3072 nt
	s_add_i32 s15, s14, s33
	s_min_i32 s16, s15, s79
	s_lshl_b32 s6, s16, 13
	s_mov_b32 s7, 0
	s_add_u32 s10, s6, 0x1000
	s_mov_b32 s11, 0
	v_lshl_add_u64 v[46:47], v[2:3], 0, s[6:7]
	v_lshl_add_u64 v[48:49], v[2:3], 0, s[10:11]
	global_load_dwordx4 v[92:95], v[46:47], off nt
	global_load_dwordx4 v[96:99], v[46:47], off offset:1024 nt
	global_load_dwordx4 v[100:103], v[46:47], off offset:2048 nt
	global_load_dwordx4 v[104:107], v[46:47], off offset:3072 nt
	global_load_dwordx4 v[108:111], v[48:49], off nt
	global_load_dwordx4 v[112:115], v[48:49], off offset:1024 nt
	global_load_dwordx4 v[116:119], v[48:49], off offset:2048 nt
	global_load_dwordx4 v[120:123], v[48:49], off offset:3072 nt
	s_lshl_b32 s16, s14, 12
	s_mov_b32 s17, 0
	v_lshl_add_u64 v[40:41], v[4:5], 0, s[16:17]
	s_waitcnt vmcnt(15)
	v_cvt_pk_bf16_f32 v57, v62, v63
	v_cvt_pk_bf16_f32 v56, v60, v61
	global_store_dwordx2 v[40:41], v[56:57], off
	v_mul_f32_e32 v7, v61, v61
	v_fmac_f32_e32 v7, v60, v60
	v_fmac_f32_e32 v7, v62, v62
	v_fmac_f32_e32 v7, v63, v63
	s_waitcnt vmcnt(15)
	v_cvt_pk_bf16_f32 v59, v66, v67
	v_cvt_pk_bf16_f32 v58, v64, v65
	global_store_dwordx2 v[40:41], v[58:59], off offset:512
	v_mul_f32_e32 v8, v65, v65
	v_fmac_f32_e32 v8, v64, v64
	v_fmac_f32_e32 v8, v66, v66
	v_fmac_f32_e32 v8, v67, v67
	v_add_f32_e32 v7, v7, v8
	s_waitcnt vmcnt(15)
	v_cvt_pk_bf16_f32 v57, v70, v71
	v_cvt_pk_bf16_f32 v56, v68, v69
	global_store_dwordx2 v[40:41], v[56:57], off offset:1024
	v_mul_f32_e32 v8, v69, v69
	v_fmac_f32_e32 v8, v68, v68
	v_fmac_f32_e32 v8, v70, v70
	v_fmac_f32_e32 v8, v71, v71
	v_add_f32_e32 v7, v7, v8
	s_waitcnt vmcnt(15)
	v_cvt_pk_bf16_f32 v59, v74, v75
	v_cvt_pk_bf16_f32 v58, v72, v73
	global_store_dwordx2 v[40:41], v[58:59], off offset:1536
	v_mul_f32_e32 v8, v73, v73
	v_fmac_f32_e32 v8, v72, v72
	v_fmac_f32_e32 v8, v74, v74
	v_fmac_f32_e32 v8, v75, v75
	v_add_f32_e32 v7, v7, v8
	s_waitcnt vmcnt(15)
	v_cvt_pk_bf16_f32 v57, v78, v79
	v_cvt_pk_bf16_f32 v56, v76, v77
	global_store_dwordx2 v[40:41], v[56:57], off offset:2048
	v_mul_f32_e32 v8, v77, v77
	v_fmac_f32_e32 v8, v76, v76
	v_fmac_f32_e32 v8, v78, v78
	v_fmac_f32_e32 v8, v79, v79
	v_add_f32_e32 v7, v7, v8
	s_waitcnt vmcnt(15)
	v_cvt_pk_bf16_f32 v59, v82, v83
	v_cvt_pk_bf16_f32 v58, v80, v81
	global_store_dwordx2 v[40:41], v[58:59], off offset:2560
	v_mul_f32_e32 v8, v81, v81
	v_fmac_f32_e32 v8, v80, v80
	v_fmac_f32_e32 v8, v82, v82
	v_fmac_f32_e32 v8, v83, v83
	v_add_f32_e32 v7, v7, v8
	s_waitcnt vmcnt(15)
	v_cvt_pk_bf16_f32 v57, v86, v87
	v_cvt_pk_bf16_f32 v56, v84, v85
	global_store_dwordx2 v[40:41], v[56:57], off offset:3072
	v_mul_f32_e32 v8, v85, v85
	v_fmac_f32_e32 v8, v84, v84
	v_fmac_f32_e32 v8, v86, v86
	v_fmac_f32_e32 v8, v87, v87
	v_add_f32_e32 v7, v7, v8
	s_waitcnt vmcnt(15)
	v_cvt_pk_bf16_f32 v59, v90, v91
	v_cvt_pk_bf16_f32 v58, v88, v89
	global_store_dwordx2 v[40:41], v[58:59], off offset:3584
	v_mul_f32_e32 v8, v89, v89
	v_fmac_f32_e32 v8, v88, v88
	v_fmac_f32_e32 v8, v90, v90
	v_fmac_f32_e32 v8, v91, v91
	v_add_f32_e32 v7, v7, v8
	ds_swizzle_b32 v8, v7 offset:swizzle(SWAP,1)
	s_waitcnt lgkmcnt(0)
	v_add_f32_e32 v7, v7, v8
	ds_swizzle_b32 v8, v7 offset:swizzle(SWAP,2)
	s_waitcnt lgkmcnt(0)
	v_add_f32_e32 v7, v7, v8
	ds_swizzle_b32 v8, v7 offset:swizzle(SWAP,4)
	s_waitcnt lgkmcnt(0)
	v_add_f32_e32 v7, v7, v8
	ds_swizzle_b32 v8, v7 offset:swizzle(SWAP,8)
	s_waitcnt lgkmcnt(0)
	v_add_f32_e32 v7, v7, v8
	ds_swizzle_b32 v8, v7 offset:swizzle(SWAP,16)
	s_waitcnt lgkmcnt(0)
	v_add_f32_e32 v7, v7, v8
	ds_bpermute_b32 v8, v6, v7
	s_lshl_b32 s16, s14, 2
	v_lshl_add_u64 v[50:51], v[44:45], 0, s[16:17]
	s_waitcnt lgkmcnt(0)
	v_add_f32_e32 v7, v7, v8
	v_cndmask_b32_e64 v7, 0, v7, s[4:5]
	s_and_saveexec_b64 s[18:19], vcc
	global_store_dword v[50:51], v7, off
	s_or_b64 exec, exec, s[18:19]
	s_cmp_gt_i32 s15, s79
	s_cbranch_scc1 .LBB0_454
; __device__ void prep_phase(KP p, char* shm) {
;   const int tid = tid_v();
;   {
;     const int wave = tid >> 6, lane = tid & 63;
;     for (int row = bid_s() * 8 + wave; row < S_; row += gridDim.x * 8) {
;       const float4* xr = (const float4*)(p->x_in + (size_t)row * D_);
;       float ss = 0.f;
; #pragma unroll
;       for (int i = 0; i < 8; ++i) {
;         float4 v = ld_nt16f((const float*)(xr + lane + 64 * i));
;         ss += v.x * v.x + v.y * v.y + v.z * v.z + v.w * v.w;
;         uint2 o; o.x = pack2(v.x, v.y); o.y = pack2(v.z, v.w);
;         *(uint2*)(p->xb + (size_t)row * D_ + (lane + 64 * i) * 4) = o;
;       }
;       ss = wave_sum(ss, lane);
;       if (lane < 32) p->rowss[(size_t)lane * S_ + row] = (lane == 0) ? ss : 0.f;
;     }
.Lmy_prep_loop:
	s_add_i32 s14, s15, s33
	s_min_i32 s16, s14, s79
	s_lshl_b32 s6, s16, 13
	s_mov_b32 s7, 0
	s_add_u32 s10, s6, 0x1000
	s_mov_b32 s11, 0
	v_lshl_add_u64 v[46:47], v[2:3], 0, s[6:7]
	v_lshl_add_u64 v[48:49], v[2:3], 0, s[10:11]
	global_load_dwordx4 v[60:63], v[46:47], off nt
	global_load_dwordx4 v[64:67], v[46:47], off offset:1024 nt
	global_load_dwordx4 v[68:71], v[46:47], off offset:2048 nt
	global_load_dwordx4 v[72:75], v[46:47], off offset:3072 nt
	global_load_dwordx4 v[76:79], v[48:49], off nt
	global_load_dwordx4 v[80:83], v[48:49], off offset:1024 nt
	global_load_dwordx4 v[84:87], v[48:49], off offset:2048 nt
	global_load_dwordx4 v[88:91], v[48:49], off offset:3072 nt
	s_lshl_b32 s16, s15, 12
	s_mov_b32 s17, 0
	v_lshl_add_u64 v[40:41], v[4:5], 0, s[16:17]
	s_waitcnt vmcnt(24)
	v_cvt_pk_bf16_f32 v57, v94, v95
	v_cvt_pk_bf16_f32 v56, v92, v93
	global_store_dwordx2 v[40:41], v[56:57], off
	v_mul_f32_e32 v7, v93, v93
	v_fmac_f32_e32 v7, v92, v92
	v_fmac_f32_e32 v7, v94, v94
	v_fmac_f32_e32 v7, v95, v95
	s_waitcnt vmcnt(24)
	v_cvt_pk_bf16_f32 v59, v98, v99
	v_cvt_pk_bf16_f32 v58, v96, v97
	global_store_dwordx2 v[40:41], v[58:59], off offset:512
	v_mul_f32_e32 v8, v97, v97
	v_fmac_f32_e32 v8, v96, v96
	v_fmac_f32_e32 v8, v98, v98
	v_fmac_f32_e32 v8, v99, v99
	v_add_f32_e32 v7, v7, v8
	s_waitcnt vmcnt(24)
	v_cvt_pk_bf16_f32 v57, v102, v103
	v_cvt_pk_bf16_f32 v56, v100, v101
	global_store_dwordx2 v[40:41], v[56:57], off offset:1024
	v_mul_f32_e32 v8, v101, v101
	v_fmac_f32_e32 v8, v100, v100
	v_fmac_f32_e32 v8, v102, v102
	v_fmac_f32_e32 v8, v103, v103
	v_add_f32_e32 v7, v7, v8
	s_waitcnt vmcnt(24)
	v_cvt_pk_bf16_f32 v59, v106, v107
	v_cvt_pk_bf16_f32 v58, v104, v105
	global_store_dwordx2 v[40:41], v[58:59], off offset:1536
	v_mul_f32_e32 v8, v105, v105
	v_fmac_f32_e32 v8, v104, v104
	v_fmac_f32_e32 v8, v106, v106
	v_fmac_f32_e32 v8, v107, v107
	v_add_f32_e32 v7, v7, v8
	s_waitcnt vmcnt(24)
	v_cvt_pk_bf16_f32 v57, v110, v111
	v_cvt_pk_bf16_f32 v56, v108, v109
	global_store_dwordx2 v[40:41], v[56:57], off offset:2048
	v_mul_f32_e32 v8, v109, v109
	v_fmac_f32_e32 v8, v108, v108
	v_fmac_f32_e32 v8, v110, v110
	v_fmac_f32_e32 v8, v111, v111
	v_add_f32_e32 v7, v7, v8
	s_waitcnt vmcnt(24)
	v_cvt_pk_bf16_f32 v59, v114, v115
	v_cvt_pk_bf16_f32 v58, v112, v113
	global_store_dwordx2 v[40:41], v[58:59], off offset:2560
	v_mul_f32_e32 v8, v113, v113
	v_fmac_f32_e32 v8, v112, v112
	v_fmac_f32_e32 v8, v114, v114
	v_fmac_f32_e32 v8, v115, v115
	v_add_f32_e32 v7, v7, v8
	s_waitcnt vmcnt(24)
	v_cvt_pk_bf16_f32 v57, v118, v119
	v_cvt_pk_bf16_f32 v56, v116, v117
	global_store_dwordx2 v[40:41], v[56:57], off offset:3072
	v_mul_f32_e32 v8, v117, v117
	v_fmac_f32_e32 v8, v116, v116
	v_fmac_f32_e32 v8, v118, v118
	v_fmac_f32_e32 v8, v119, v119
	v_add_f32_e32 v7, v7, v8
	s_waitcnt vmcnt(24)
	v_cvt_pk_bf16_f32 v59, v122, v123
	v_cvt_pk_bf16_f32 v58, v120, v121
	global_store_dwordx2 v[40:41], v[58:59], off offset:3584
	v_mul_f32_e32 v8, v121, v121
	v_fmac_f32_e32 v8, v120, v120
	v_fmac_f32_e32 v8, v122, v122
	v_fmac_f32_e32 v8, v123, v123
	v_add_f32_e32 v7, v7, v8
	ds_swizzle_b32 v8, v7 offset:swizzle(SWAP,1)
	s_waitcnt lgkmcnt(0)
	v_add_f32_e32 v7, v7, v8
	ds_swizzle_b32 v8, v7 offset:swizzle(SWAP,2)
	s_waitcnt lgkmcnt(0)
	v_add_f32_e32 v7, v7, v8
	ds_swizzle_b32 v8, v7 offset:swizzle(SWAP,4)
	s_waitcnt lgkmcnt(0)
	v_add_f32_e32 v7, v7, v8
	ds_swizzle_b32 v8, v7 offset:swizzle(SWAP,8)
	s_waitcnt lgkmcnt(0)
	v_add_f32_e32 v7, v7, v8
	ds_swizzle_b32 v8, v7 offset:swizzle(SWAP,16)
	s_waitcnt lgkmcnt(0)
	v_add_f32_e32 v7, v7, v8
	ds_bpermute_b32 v8, v6, v7
	s_lshl_b32 s16, s15, 2
	v_lshl_add_u64 v[50:51], v[44:45], 0, s[16:17]
	s_waitcnt lgkmcnt(0)
	v_add_f32_e32 v7, v7, v8
	v_cndmask_b32_e64 v7, 0, v7, s[4:5]
	s_and_saveexec_b64 s[18:19], vcc
	global_store_dword v[50:51], v7, off
	s_or_b64 exec, exec, s[18:19]
	s_cmp_gt_i32 s14, s79
	s_cbranch_scc1 .LBB0_454
; __device__ void prep_phase(KP p, char* shm) {
;   const int tid = tid_v();
;   {
;     const int wave = tid >> 6, lane = tid & 63;
;     for (int row = bid_s() * 8 + wave; row < S_; row += gridDim.x * 8) {
;       const float4* xr = (const float4*)(p->x_in + (size_t)row * D_);
;       float ss = 0.f;
; #pragma unroll
;       for (int i = 0; i < 8; ++i) {
;         float4 v = ld_nt16f((const float*)(xr + lane + 64 * i));
;         ss += v.x * v.x + v.y * v.y + v.z * v.z + v.w * v.w;
;         uint2 o; o.x = pack2(v.x, v.y); o.y = pack2(v.z, v.w);
;         *(uint2*)(p->xb + (size_t)row * D_ + (lane + 64 * i) * 4) = o;
;       }
;       ss = wave_sum(ss, lane);
;       if (lane < 32) p->rowss[(size_t)lane * S_ + row] = (lane == 0) ? ss : 0.f;
;     }
	s_add_i32 s15, s14, s33
	s_min_i32 s16, s15, s79
	s_lshl_b32 s6, s16, 13
	s_mov_b32 s7, 0
	s_add_u32 s10, s6, 0x1000
	s_mov_b32 s11, 0
	v_lshl_add_u64 v[46:47], v[2:3], 0, s[6:7]
	v_lshl_add_u64 v[48:49], v[2:3], 0, s[10:11]
	global_load_dwordx4 v[92:95], v[46:47], off nt
	global_load_dwordx4 v[96:99], v[46:47], off offset:1024 nt
	global_load_dwordx4 v[100:103], v[46:47], off offset:2048 nt
	global_load_dwordx4 v[104:107], v[46:47], off offset:3072 nt
	global_load_dwordx4 v[108:111], v[48:49], off nt
	global_load_dwordx4 v[112:115], v[48:49], off offset:1024 nt
	global_load_dwordx4 v[116:119], v[48:49], off offset:2048 nt
	global_load_dwordx4 v[120:123], v[48:49], off offset:3072 nt
	s_lshl_b32 s16, s14, 12
	s_mov_b32 s17, 0
	v_lshl_add_u64 v[40:41], v[4:5], 0, s[16:17]
	s_waitcnt vmcnt(24)
	v_cvt_pk_bf16_f32 v57, v62, v63
	v_cvt_pk_bf16_f32 v56, v60, v61
	global_store_dwordx2 v[40:41], v[56:57], off
	v_mul_f32_e32 v7, v61, v61
	v_fmac_f32_e32 v7, v60, v60
	v_fmac_f32_e32 v7, v62, v62
	v_fmac_f32_e32 v7, v63, v63
	s_waitcnt vmcnt(24)
	v_cvt_pk_bf16_f32 v59, v66, v67
	v_cvt_pk_bf16_f32 v58, v64, v65
	global_store_dwordx2 v[40:41], v[58:59], off offset:512
	v_mul_f32_e32 v8, v65, v65
	v_fmac_f32_e32 v8, v64, v64
	v_fmac_f32_e32 v8, v66, v66
	v_fmac_f32_e32 v8, v67, v67
	v_add_f32_e32 v7, v7, v8
	s_waitcnt vmcnt(24)
	v_cvt_pk_bf16_f32 v57, v70, v71
	v_cvt_pk_bf16_f32 v56, v68, v69
	global_store_dwordx2 v[40:41], v[56:57], off offset:1024
	v_mul_f32_e32 v8, v69, v69
	v_fmac_f32_e32 v8, v68, v68
	v_fmac_f32_e32 v8, v70, v70
	v_fmac_f32_e32 v8, v71, v71
	v_add_f32_e32 v7, v7, v8
	s_waitcnt vmcnt(24)
	v_cvt_pk_bf16_f32 v59, v74, v75
	v_cvt_pk_bf16_f32 v58, v72, v73
	global_store_dwordx2 v[40:41], v[58:59], off offset:1536
	v_mul_f32_e32 v8, v73, v73
	v_fmac_f32_e32 v8, v72, v72
	v_fmac_f32_e32 v8, v74, v74
	v_fmac_f32_e32 v8, v75, v75
	v_add_f32_e32 v7, v7, v8
	s_waitcnt vmcnt(24)
	v_cvt_pk_bf16_f32 v57, v78, v79
	v_cvt_pk_bf16_f32 v56, v76, v77
	global_store_dwordx2 v[40:41], v[56:57], off offset:2048
	v_mul_f32_e32 v8, v77, v77
	v_fmac_f32_e32 v8, v76, v76
	v_fmac_f32_e32 v8, v78, v78
	v_fmac_f32_e32 v8, v79, v79
	v_add_f32_e32 v7, v7, v8
	s_waitcnt vmcnt(24)
	v_cvt_pk_bf16_f32 v59, v82, v83
	v_cvt_pk_bf16_f32 v58, v80, v81
	global_store_dwordx2 v[40:41], v[58:59], off offset:2560
	v_mul_f32_e32 v8, v81, v81
	v_fmac_f32_e32 v8, v80, v80
	v_fmac_f32_e32 v8, v82, v82
	v_fmac_f32_e32 v8, v83, v83
	v_add_f32_e32 v7, v7, v8
	s_waitcnt vmcnt(24)
	v_cvt_pk_bf16_f32 v57, v86, v87
	v_cvt_pk_bf16_f32 v56, v84, v85
	global_store_dwordx2 v[40:41], v[56:57], off offset:3072
	v_mul_f32_e32 v8, v85, v85
	v_fmac_f32_e32 v8, v84, v84
	v_fmac_f32_e32 v8, v86, v86
	v_fmac_f32_e32 v8, v87, v87
	v_add_f32_e32 v7, v7, v8
	s_waitcnt vmcnt(24)
	v_cvt_pk_bf16_f32 v59, v90, v91
	v_cvt_pk_bf16_f32 v58, v88, v89
	global_store_dwordx2 v[40:41], v[58:59], off offset:3584
	v_mul_f32_e32 v8, v89, v89
	v_fmac_f32_e32 v8, v88, v88
	v_fmac_f32_e32 v8, v90, v90
	v_fmac_f32_e32 v8, v91, v91
	v_add_f32_e32 v7, v7, v8
	ds_swizzle_b32 v8, v7 offset:swizzle(SWAP,1)
	s_waitcnt lgkmcnt(0)
	v_add_f32_e32 v7, v7, v8
	ds_swizzle_b32 v8, v7 offset:swizzle(SWAP,2)
	s_waitcnt lgkmcnt(0)
	v_add_f32_e32 v7, v7, v8
	ds_swizzle_b32 v8, v7 offset:swizzle(SWAP,4)
	s_waitcnt lgkmcnt(0)
	v_add_f32_e32 v7, v7, v8
	ds_swizzle_b32 v8, v7 offset:swizzle(SWAP,8)
	s_waitcnt lgkmcnt(0)
	v_add_f32_e32 v7, v7, v8
	ds_swizzle_b32 v8, v7 offset:swizzle(SWAP,16)
	s_waitcnt lgkmcnt(0)
	v_add_f32_e32 v7, v7, v8
	ds_bpermute_b32 v8, v6, v7
	s_lshl_b32 s16, s14, 2
	v_lshl_add_u64 v[50:51], v[44:45], 0, s[16:17]
	s_waitcnt lgkmcnt(0)
	v_add_f32_e32 v7, v7, v8
	v_cndmask_b32_e64 v7, 0, v7, s[4:5]
	s_and_saveexec_b64 s[18:19], vcc
	global_store_dword v[50:51], v7, off
	s_or_b64 exec, exec, s[18:19]
	s_cmp_gt_i32 s15, s79
	s_cbranch_scc0 .Lmy_prep_loop
